# speedup vs baseline: 1.0331x; 1.0107x over previous
; template <int EPI> ...
;     ...
;   for (int i = 0; i < nA + nB; ++i) {
;     int pm, pn, koff;
;     bool atom;
;     tile_desc(i, pm, pn, koff, atom);
;     const int kk = atom ? Kc : K;
;     int brow = pm * 256, bcol = pn * 256;
;     void* o = outp;
;     int orow = brow;
;     if (EPI == 0) {
;       if (brow < USPLIT) {
;         o = (void*)p.out;
;       } else {
;         o = (void*)(p.ws + OFF_X);
;         orow = brow - USPLIT;
;       }
;     }
;     if (EPI == 1 && atom) {
;       o = (void*)((float*)(p.ws + OFF_PART) + (long)(koff / Kc) * (256 * DM));
;       orow = 0;
;     }
;     const char* nAb = nullptr;
;     const char* nBb = nullptr;
;     if (i + 1 < nA + nB) {
;       int pm2, pn2, koff2;
;       bool atom2;
;       tile_desc(i + 1, pm2, pn2, koff2, atom2);
;       nAb = (const char*)(A + koff2 + (long)pm2 * 256 * K);
;       nBb = (const char*)(Bt + koff2 + (long)pn2 * 256 * K);
;     }
;     gemm_tile<EPI>(A + koff, Bt + koff, kk, brow, bcol, o, orow, ldo, shm, ss_in, gain_out, atom ? nullptr : nout,
;                    ss_out, K, atom, pre, nAb, nBb);
.LBB0_103:
	s_mul_i32 s2, s59, s1
	s_add_i32 s2, s2, s34
	s_add_i32 s59, s59, 1
	s_cmp_ge_i32 s59, s33
	s_mov_b64 s[88:89], 0
	s_mov_b64 s[92:93], 0
	s_cbranch_scc1 .LBB0_105
	s_add_i32 s6, s2, s1
	s_ashr_i32 s7, s6, 31
	s_lshr_b32 s7, s7, 25
	s_add_i32 s7, s6, s7
	s_ashr_i32 s8, s7, 7
	s_lshl_b32 s8, s8, 2
	s_sub_i32 s9, s0, s8
	s_min_i32 s9, s9, 4
	s_abs_i32 s10, s9
	v_cvt_f32_u32_e32 v0, s10
	s_sub_i32 s20, 0, s10
	s_and_b32 s7, s7, 0xffffff80
	s_sub_i32 s7, s6, s7
	v_rcp_iflag_f32_e32 v0, v0
	s_abs_i32 s6, s7
	s_xor_b32 s11, s7, s9
	s_ashr_i32 s11, s11, 31
	v_mul_f32_e32 v0, 0x4f7ffffe, v0
	v_cvt_u32_f32_e32 v0, v0
	s_nop 0
	v_readfirstlane_b32 s21, v0
	s_mul_i32 s20, s20, s21
	s_mul_hi_u32 s20, s21, s20
	s_add_i32 s21, s21, s20
	s_mul_hi_u32 s20, s6, s21
	s_mul_i32 s21, s20, s10
	s_sub_i32 s6, s6, s21
	s_add_i32 s22, s20, 1
	s_sub_i32 s21, s6, s10
	s_cmp_ge_u32 s6, s10
	s_cselect_b32 s20, s22, s20
	s_cselect_b32 s6, s21, s6
	s_add_i32 s21, s20, 1
	s_cmp_ge_u32 s6, s10
	s_cselect_b32 s6, s21, s20
	s_xor_b32 s6, s6, s11
	s_sub_i32 s6, s6, s11
	s_mul_i32 s9, s6, s9
	s_sub_i32 s7, s7, s9
	s_add_i32 s8, s7, s8
	s_ashr_i32 s9, s8, 31
	s_lshl_b64 s[8:9], s[8:9], 20
	s_add_u32 s88, s47, s8
	s_addc_u32 s89, s48, s9
	s_ashr_i32 s7, s6, 31
	s_lshl_b64 s[6:7], s[6:7], 20
	s_add_u32 s92, s57, s6
	s_addc_u32 s93, s58, s7
.LBB0_105:
	s_ashr_i32 s6, s2, 31
	s_lshr_b32 s6, s6, 25
	s_add_i32 s6, s2, s6
	s_ashr_i32 s7, s6, 7
	s_lshl_b32 s7, s7, 2
	s_sub_i32 s8, s0, s7
	s_min_i32 s10, s8, 4
	s_abs_i32 s11, s10
	v_cvt_f32_u32_e32 v0, s11
	s_xor_b64 s[8:9], s[12:13], -1
	s_sub_i32 s13, 0, s11
	s_and_b32 s6, s6, 0xffffff80
	v_rcp_iflag_f32_e32 v0, v0
	s_sub_i32 s2, s2, s6
	s_abs_i32 s6, s2
	s_xor_b32 s12, s2, s10
	v_mul_f32_e32 v0, 0x4f7ffffe, v0
	v_cvt_u32_f32_e32 v0, v0
	s_ashr_i32 s12, s12, 31
	v_mov_b32_e32 v134, v193
	v_readfirstlane_b32 s20, v0
	s_mul_i32 s13, s13, s20
	s_mul_hi_u32 s13, s20, s13
	s_add_i32 s20, s20, s13
	s_mul_hi_u32 s13, s6, s20
	s_mul_i32 s20, s13, s11
	s_sub_i32 s6, s6, s20
	s_add_i32 s21, s13, 1
	s_sub_i32 s20, s6, s11
	s_cmp_ge_u32 s6, s11
	s_cselect_b32 s13, s21, s13
	s_cselect_b32 s6, s20, s6
	s_add_i32 s20, s13, 1
	s_cmp_ge_u32 s6, s11
	s_cselect_b32 s6, s20, s13
	s_xor_b32 s6, s6, s12
	s_sub_i32 s6, s6, s12
	s_mul_i32 s10, s6, s10
	s_sub_i32 s2, s2, s10
	s_add_i32 s7, s7, s2
	s_lshl_b32 s94, s7, 8
	s_lshl_b32 s90, s6, 8
	v_readfirstlane_b32 s2, v134
	s_lshl_b32 s2, s2, 4
	s_ashr_i32 s95, s94, 31
	s_ashr_i32 s91, s90, 31
	s_and_b32 s6, s2, 0x1c00
	s_lshl_b64 s[10:11], s[94:95], 12
	s_lshl_b64 s[12:13], s[90:91], 12
	s_cmp_lg_u32 0, -1
	s_cselect_b32 s2, 0, 0
	v_lshlrev_b32_e32 v2, 4, v134
	v_and_b32_e32 v3, 32, v134
	s_add_i32 s2, s6, s2
	v_lshrrev_b32_e32 v4, 3, v134
	v_bfe_u32 v5, v134, 2, 4
	v_bitop3_b32 v2, v2, v3, 48 bitop3:0x6c
	s_add_u32 s96, s47, s10
	v_and_or_b32 v2, v134, 64, v2
	v_and_or_b32 v3, v4, 48, v5
	s_addc_u32 s97, s48, s11
	v_ashrrev_i32_e32 v0, 8, v134
	v_lshl_or_b32 v132, v3, 12, v2
	s_add_u32 s98, s57, s12
	v_or_b32_e32 v130, 0x40000, v132
	s_addc_u32 s99, s58, s13
	s_mov_b64 s[50:51], -1
	s_andn2_b64 vcc, exec, s[8:9]
	v_cmp_eq_u32_e64 s[12:13], 1, v0
	s_cbranch_vccnz .LBB0_109
	s_cmp_lg_u32 0, -1
	s_cselect_b32 s7, 0, 0
	s_add_i32 s7, s7, s6
	s_add_i32 s20, s7, 0x10000
	s_mov_b32 m0, s20
	s_nop 0
	global_load_lds_dwordx4 v132, s[98:99]
	s_add_i32 s21, s7, 0x12000
	s_mov_b32 m0, s21
	s_nop 0
	global_load_lds_dwordx4 v130, s[98:99]
	s_add_i32 s38, s7, 0x2000
	s_mov_b32 m0, s2
	s_nop 0
	global_load_lds_dwordx4 v132, s[96:97]
	s_add_u32 s8, s98, 0x80000
	s_mov_b32 m0, s38
	s_nop 0
	global_load_lds_dwordx4 v130, s[96:97]
	s_addc_u32 s9, s99, 0
	s_add_i32 s39, s7, 0x14000
	s_mov_b32 m0, s39
	s_nop 0
	global_load_lds_dwordx4 v132, s[8:9]
	s_add_i32 s28, s7, 0x16000
	s_mov_b32 m0, s28
	s_nop 0
	global_load_lds_dwordx4 v130, s[8:9]
	s_add_u32 s8, s96, 0x80000
	s_addc_u32 s9, s97, 0
	s_add_i32 s29, s7, 0x4000
	s_mov_b32 m0, s29
	s_nop 0
	global_load_lds_dwordx4 v132, s[8:9]
	s_add_i32 s62, s7, 0x6000
	s_mov_b32 m0, s62
	s_nop 0
	global_load_lds_dwordx4 v130, s[8:9]
	s_and_saveexec_b64 s[50:51], s[12:13]
	s_cbranch_execz .LBB0_108
	s_barrier

; template <int EPI> ...
;     ...
;   auto tile_desc = [&](int i, int& pm, int& pn, int& koff, bool& atom) {
;     koff = 0;
;     atom = false;
;     if (i < nA) {
;       tile_coords(startA + jA + i * perA, nM, nN, pm, pn);
;     } else {
;       int u = startB + jB + (i - nA) * perB;
;       pm = mini_pm;
;       pn = u % nN;
;       koff = (u / nN) * Kc;
;       atom = true;
;     }
;   };
.LBB0_182:
	s_cmp_ge_i32 s99, s95
	s_cselect_b64 s[82:83], -1, 0
	s_cmp_lt_i32 s99, s95
	s_mov_b64 s[40:41], -1
	s_cselect_b64 s[84:85], -1, 0
	s_and_b64 vcc, exec, s[82:83]
	s_cbranch_vccnz .LBB0_184
	s_mul_i32 s2, s99, s94
	s_add_i32 s2, s2, s58
	s_ashr_i32 s6, s2, 31
	s_lshr_b32 s6, s6, 27
	s_add_i32 s6, s2, s6
	s_ashr_i32 s7, s6, 5
	s_lshl_b32 s7, s7, 2
	s_sub_i32 s8, s77, s7
	s_min_i32 s8, s8, 4
	s_abs_i32 s9, s8
	v_cvt_f32_u32_e32 v0, s9
	s_sub_i32 s11, 0, s9
	s_andn2_b32 s6, s6, 31
	s_sub_i32 s6, s2, s6
	v_rcp_iflag_f32_e32 v0, v0
	s_abs_i32 s2, s6
	s_xor_b32 s10, s6, s8
	s_ashr_i32 s10, s10, 31
	v_mul_f32_e32 v0, 0x4f7ffffe, v0
	v_cvt_u32_f32_e32 v0, v0
	s_mov_b64 s[40:41], 0
	v_readfirstlane_b32 s20, v0
	s_mul_i32 s11, s11, s20
	s_mul_hi_u32 s11, s20, s11
	s_add_i32 s20, s20, s11
	s_mul_hi_u32 s11, s2, s20
	s_mul_i32 s20, s11, s9
	s_sub_i32 s2, s2, s20
	s_add_i32 s21, s11, 1
	s_sub_i32 s20, s2, s9
	s_cmp_ge_u32 s2, s9
	s_cselect_b32 s11, s21, s11
	s_cselect_b32 s2, s20, s2
	s_add_i32 s20, s11, 1
	s_cmp_ge_u32 s2, s9
	s_cselect_b32 s2, s20, s11
	s_xor_b32 s2, s2, s10
	s_sub_i32 s2, s2, s10
	s_mul_i32 s8, s2, s8
	s_sub_i32 s6, s6, s8
	s_add_i32 s7, s6, s7

; template <int EPI> ...
;     ...
;   auto tile_desc = [&](int i, int& pm, int& pn, int& koff, bool& atom) {
;     koff = 0;
;     atom = false;
;     if (i < nA) {
;       tile_coords(startA + jA + i * perA, nM, nN, pm, pn);
;     } else {
;       int u = startB + jB + (i - nA) * perB;
;       pm = mini_pm;
;       pn = u % nN;
;       koff = (u / nN) * Kc;
;       atom = true;
;     }
;   };
.LBB0_191:
	s_andn2_b64 vcc, exec, s[50:51]
	s_mov_b32 s8, s56
	s_cbranch_vccnz .LBB0_193
	s_mul_i32 s7, s99, s94
	s_add_i32 s7, s7, s58
	s_ashr_i32 s8, s7, 31
	s_lshr_b32 s8, s8, 27
	s_add_i32 s8, s7, s8
	s_ashr_i32 s9, s8, 5
	s_lshl_b32 s9, s9, 2
	s_sub_i32 s10, s77, s9
	s_min_i32 s10, s10, 4
	s_abs_i32 s11, s10
	v_cvt_f32_u32_e32 v0, s11
	s_sub_i32 s21, 0, s11
	s_andn2_b32 s8, s8, 31
	s_sub_i32 s8, s7, s8
	v_rcp_iflag_f32_e32 v0, v0
	s_abs_i32 s7, s8
	s_xor_b32 s20, s8, s10
	s_ashr_i32 s20, s20, 31
	v_mul_f32_e32 v0, 0x4f7ffffe, v0
	v_cvt_u32_f32_e32 v0, v0
	s_mov_b64 s[40:41], 0
	v_readfirstlane_b32 s28, v0
	s_mul_i32 s21, s21, s28
	s_mul_hi_u32 s21, s28, s21
	s_add_i32 s28, s28, s21
	s_mul_hi_u32 s21, s7, s28
	s_mul_i32 s28, s21, s11
	s_sub_i32 s7, s7, s28
	s_add_i32 s29, s21, 1
	s_sub_i32 s28, s7, s11
	s_cmp_ge_u32 s7, s11
	s_cselect_b32 s21, s29, s21
	s_cselect_b32 s7, s28, s7
	s_add_i32 s28, s21, 1
	s_cmp_ge_u32 s7, s11
	s_cselect_b32 s7, s28, s21
	s_xor_b32 s7, s7, s20
	s_sub_i32 s7, s7, s20
	s_mul_i32 s10, s7, s10
	s_sub_i32 s8, s8, s10
	s_add_i32 s8, s8, s9

; template <int EPI> ...
;     ...
;   for (int i = 0; i < nA + nB; ++i) {
;     int pm, pn, koff;
;     bool atom;
;     tile_desc(i, pm, pn, koff, atom);
;     const int kk = atom ? Kc : K;
;     int brow = pm * 256, bcol = pn * 256;
;     void* o = outp;
;     int orow = brow;
;     if (EPI == 0) {
;       if (brow < USPLIT) {
;         o = (void*)p.out;
;       } else {
;         o = (void*)(p.ws + OFF_X);
;         orow = brow - USPLIT;
;       }
;     }
;     if (EPI == 1 && atom) {
;       o = (void*)((float*)(p.ws + OFF_PART) + (long)(koff / Kc) * (256 * DM));
;       orow = 0;
;     }
;     const char* nAb = nullptr;
;     const char* nBb = nullptr;
;     if (i + 1 < nA + nB) {
;       int pm2, pn2, koff2;
;       bool atom2;
;       tile_desc(i + 1, pm2, pn2, koff2, atom2);
;       nAb = (const char*)(A + koff2 + (long)pm2 * 256 * K);
;       nBb = (const char*)(Bt + koff2 + (long)pn2 * 256 * K);
;     }
;     gemm_tile<EPI>(A + koff, Bt + koff, kk, brow, bcol, o, orow, ldo, shm, ss_in, gain_out, atom ? nullptr : nout,
;                    ss_out, K, atom, pre, nAb, nBb);
.LBB0_404:
	s_mul_i32 s0, s76, s34
	s_add_i32 s0, s0, s77
	s_add_i32 s76, s76, 1
	s_cmp_ge_i32 s76, s49
	s_mov_b64 s[28:29], 0
	s_mov_b64 s[16:17], 0
	s_cbranch_scc1 .LBB0_406
	s_add_i32 s1, s0, s34
	s_mul_hi_i32 s2, s1, 0x2aaaaaab
	s_lshr_b32 s6, s2, 31
	s_ashr_i32 s2, s2, 4
	s_add_i32 s2, s2, s6
	s_lshl_b32 s7, s2, 2
	s_sub_i32 s6, 0xc1, s7
	s_min_i32 s8, s6, 4
	s_abs_i32 s6, s8
	v_cvt_f32_u32_e32 v0, s6
	s_sub_i32 s10, 0, s6
	s_mulk_i32 s2, 0x60
	s_sub_i32 s1, s1, s2
	v_rcp_iflag_f32_e32 v0, v0
	s_abs_i32 s2, s1
	s_xor_b32 s9, s1, s8
	s_ashr_i32 s9, s9, 31
	v_mul_f32_e32 v0, 0x4f7ffffe, v0
	v_cvt_u32_f32_e32 v0, v0
	s_nop 0
	v_readfirstlane_b32 s11, v0
	s_mul_i32 s10, s10, s11
	s_mul_hi_u32 s10, s11, s10
	s_add_i32 s11, s11, s10
	s_mul_hi_u32 s10, s2, s11
	s_mul_i32 s11, s10, s6
	s_sub_i32 s2, s2, s11
	s_add_i32 s14, s10, 1
	s_sub_i32 s11, s2, s6
	s_cmp_ge_u32 s2, s6
	s_cselect_b32 s10, s14, s10
	s_cselect_b32 s2, s11, s2
	s_add_i32 s11, s10, 1
	s_cmp_ge_u32 s2, s6
	s_cselect_b32 s2, s11, s10
	s_xor_b32 s2, s2, s9
	s_sub_i32 s6, s2, s9
	s_mul_i32 s2, s6, s8
	s_sub_i32 s1, s1, s2
	s_add_i32 s8, s1, s7
	s_ashr_i32 s9, s8, 31
	s_lshl_b64 s[8:9], s[8:9], 20
	s_add_u32 s28, s68, s8
	s_addc_u32 s29, s69, s9
	s_ashr_i32 s7, s6, 31
	s_lshl_b64 s[6:7], s[6:7], 20
	s_add_u32 s16, s56, s6
	s_addc_u32 s17, s57, s7
.LBB0_406:
	s_mul_hi_i32 s1, s0, 0x2aaaaaab
	s_lshr_b32 s2, s1, 31
	s_ashr_i32 s1, s1, 4
	s_add_i32 s1, s1, s2
	s_lshl_b32 s2, s1, 2
	s_sub_i32 s6, 0xc1, s2
	s_min_i32 s6, s6, 4
	s_abs_i32 s7, s6
	v_cvt_f32_u32_e32 v0, s7
	s_xor_b64 s[8:9], s[12:13], -1
	s_sub_i32 s11, 0, s7
	s_mulk_i32 s1, 0x60
	v_rcp_iflag_f32_e32 v0, v0
	s_sub_i32 s0, s0, s1
	s_abs_i32 s1, s0
	s_xor_b32 s10, s0, s6
	v_mul_f32_e32 v0, 0x4f7ffffe, v0
	v_cvt_u32_f32_e32 v0, v0
	s_ashr_i32 s10, s10, 31
	v_mov_b32_e32 v133, v193
	v_readfirstlane_b32 s12, v0
	s_mul_i32 s11, s11, s12
	s_mul_hi_u32 s11, s12, s11
	s_add_i32 s12, s12, s11
	s_mul_hi_u32 s11, s1, s12
	s_mul_i32 s12, s11, s7
	s_sub_i32 s1, s1, s12
	s_add_i32 s13, s11, 1
	s_sub_i32 s12, s1, s7
	s_cmp_ge_u32 s1, s7
	s_cselect_b32 s11, s13, s11
	s_cselect_b32 s1, s12, s1
	s_add_i32 s12, s11, 1
	s_cmp_ge_u32 s1, s7
	s_cselect_b32 s1, s12, s11
	s_xor_b32 s1, s1, s10
	s_sub_i32 s1, s1, s10
	s_mul_i32 s6, s1, s6
	s_sub_i32 s0, s0, s6
	s_add_i32 s0, s2, s0
	s_lshl_b32 s40, s0, 8
	s_lshl_b32 s14, s1, 8
	v_readfirstlane_b32 s2, v133
	s_lshl_b32 s2, s2, 4
	s_ashr_i32 s41, s40, 31
	s_ashr_i32 s15, s14, 31
	s_and_b32 s6, s2, 0x1c00
	s_lshl_b64 s[10:11], s[40:41], 12
	s_lshl_b64 s[12:13], s[14:15], 12
	s_cmp_lg_u32 0, -1
	s_cselect_b32 s2, 0, 0
	v_lshlrev_b32_e32 v0, 4, v133
	v_and_b32_e32 v2, 32, v133
	s_add_i32 s2, s6, s2
	v_lshrrev_b32_e32 v3, 3, v133
	v_bfe_u32 v4, v133, 2, 4
	v_bitop3_b32 v0, v0, v2, 48 bitop3:0x6c
	s_add_u32 s18, s68, s10
	v_and_or_b32 v0, v133, 64, v0
	v_and_or_b32 v2, v3, 48, v4
	s_addc_u32 s19, s69, s11
	v_ashrrev_i32_e32 v130, 8, v133
	v_lshl_or_b32 v132, v2, 12, v0
	s_add_u32 s72, s56, s12
	v_or_b32_e32 v131, 0x40000, v132
	s_addc_u32 s73, s57, s13
	s_mov_b64 s[74:75], -1
	s_andn2_b64 vcc, exec, s[8:9]
	v_cmp_eq_u32_e64 s[12:13], 1, v130
	s_cbranch_vccnz .LBB0_410
	s_cmp_lg_u32 0, -1
	s_cselect_b32 s7, 0, 0
	s_add_i32 s7, s7, s6
	s_add_i32 s15, s7, 0x10000
	s_mov_b32 m0, s15
	s_nop 0
	global_load_lds_dwordx4 v132, s[72:73]
	s_add_i32 s33, s7, 0x12000
	s_mov_b32 m0, s33
	s_nop 0
	global_load_lds_dwordx4 v131, s[72:73]
	s_add_i32 s41, s7, 0x2000
	s_mov_b32 m0, s2
	s_nop 0
	global_load_lds_dwordx4 v132, s[18:19]
	s_add_u32 s8, s72, 0x80000
	s_mov_b32 m0, s41
	s_nop 0
	global_load_lds_dwordx4 v131, s[18:19]
	s_addc_u32 s9, s73, 0
	s_add_i32 s38, s7, 0x14000
	s_mov_b32 m0, s38
	s_nop 0
	global_load_lds_dwordx4 v132, s[8:9]
	s_add_i32 s39, s7, 0x16000
	s_mov_b32 m0, s39
	s_nop 0
	global_load_lds_dwordx4 v131, s[8:9]
	s_add_u32 s8, s18, 0x80000
	s_addc_u32 s9, s19, 0
	s_add_i32 s47, s7, 0x4000
	s_mov_b32 m0, s47
	s_nop 0
	global_load_lds_dwordx4 v132, s[8:9]
	s_add_i32 s48, s7, 0x6000
	s_mov_b32 m0, s48
	s_nop 0
	global_load_lds_dwordx4 v131, s[8:9]
	s_and_saveexec_b64 s[50:51], s[12:13]
	s_cbranch_execz .LBB0_409
	s_barrier
